# LRU scan pass 2: store row addresses formed on the scalar unit
# speedup vs baseline: 1.0139x; 1.0123x over previous
; __device__ __forceinline__ bf16_t f2bf(float f) { return (bf16_t)(pk2(f, 0.f) & 0xffffu); }
; __device__ __forceinline__ void lru_item(const Args& A, Frame& F, int l, int it) {
;     ...
; #pragma unroll
;             for (int i = 0; i < 16; ++i) {
;                 const int si = 16 * seg + i; const float a = as[si * 64 + ch], bb = us[si * 64 + ch];
;                 hv = a * hv + bb;
;                 const int p = dir == 0 ? pbase + si : pbase - si;
;                 hout[(size_t)p * D + ch] = f2bf(hv);
;             }
;             if (seg == 7) hcar[((sc + 1) & 1) * 64 + ch] = hv;
.Lmy_lru_comb_done:
	v_readfirstlane_b32 s98, v60
	v_readfirstlane_b32 s99, v61
	v_readfirstlane_b32 s100, v97
	s_and_b64 vcc, s[8:9], exec
	s_movk_i32 s101, 0xf800
	s_cselect_b32 s101, 0x800, s101
	s_add_i32 s100, s100, s39
	s_lshl_b32 s100, s100, 11
	v_lshlrev_b32_e32 v24, 1, v102
	v_fma_f32 v22, v22, v190, v206
	v_cvt_pk_bf16_f32 v23, v22, s0
	s_add_u32 vcc_lo, s98, s100
	s_addc_u32 vcc_hi, s99, 0
	global_store_short v24, v23, vcc
	s_add_i32 s100, s100, s101
	v_fma_f32 v22, v22, v191, v207
	v_cvt_pk_bf16_f32 v239, v22, s0
	s_add_u32 vcc_lo, s98, s100
	s_addc_u32 vcc_hi, s99, 0
	global_store_short v24, v239, vcc
	s_add_i32 s100, s100, s101
	v_fma_f32 v22, v22, v192, v208
	v_cvt_pk_bf16_f32 v23, v22, s0
	s_add_u32 vcc_lo, s98, s100
	s_addc_u32 vcc_hi, s99, 0
	global_store_short v24, v23, vcc
	s_add_i32 s100, s100, s101
	v_fma_f32 v22, v22, v193, v209
	v_cvt_pk_bf16_f32 v239, v22, s0
	s_add_u32 vcc_lo, s98, s100
	s_addc_u32 vcc_hi, s99, 0
	global_store_short v24, v239, vcc
	s_add_i32 s100, s100, s101
	v_fma_f32 v22, v22, v194, v210
	v_cvt_pk_bf16_f32 v23, v22, s0
	s_add_u32 vcc_lo, s98, s100
	s_addc_u32 vcc_hi, s99, 0
	global_store_short v24, v23, vcc
	s_add_i32 s100, s100, s101
	v_fma_f32 v22, v22, v195, v211
	v_cvt_pk_bf16_f32 v239, v22, s0
	s_add_u32 vcc_lo, s98, s100
	s_addc_u32 vcc_hi, s99, 0
	global_store_short v24, v239, vcc
	s_add_i32 s100, s100, s101
	v_fma_f32 v22, v22, v196, v212
	v_cvt_pk_bf16_f32 v23, v22, s0
	s_add_u32 vcc_lo, s98, s100
	s_addc_u32 vcc_hi, s99, 0
	global_store_short v24, v23, vcc
	s_add_i32 s100, s100, s101
	v_fma_f32 v22, v22, v197, v213
	v_cvt_pk_bf16_f32 v239, v22, s0
	s_add_u32 vcc_lo, s98, s100
	s_addc_u32 vcc_hi, s99, 0
	global_store_short v24, v239, vcc
	s_add_i32 s100, s100, s101
	v_fma_f32 v22, v22, v198, v214
	v_cvt_pk_bf16_f32 v23, v22, s0
	s_add_u32 vcc_lo, s98, s100
	s_addc_u32 vcc_hi, s99, 0
	global_store_short v24, v23, vcc
	s_add_i32 s100, s100, s101
	v_fma_f32 v22, v22, v199, v215
	v_cvt_pk_bf16_f32 v239, v22, s0
	s_add_u32 vcc_lo, s98, s100
	s_addc_u32 vcc_hi, s99, 0
	global_store_short v24, v239, vcc
	s_add_i32 s100, s100, s101
	v_fma_f32 v22, v22, v200, v216
	v_cvt_pk_bf16_f32 v23, v22, s0
	s_add_u32 vcc_lo, s98, s100
	s_addc_u32 vcc_hi, s99, 0
	global_store_short v24, v23, vcc
	s_add_i32 s100, s100, s101
	v_fma_f32 v22, v22, v201, v217
	v_cvt_pk_bf16_f32 v239, v22, s0
	s_add_u32 vcc_lo, s98, s100
	s_addc_u32 vcc_hi, s99, 0
	global_store_short v24, v239, vcc
	s_add_i32 s100, s100, s101
	v_fma_f32 v22, v22, v202, v218
	v_cvt_pk_bf16_f32 v23, v22, s0
	s_add_u32 vcc_lo, s98, s100
	s_addc_u32 vcc_hi, s99, 0
	global_store_short v24, v23, vcc
	s_add_i32 s100, s100, s101
	v_fma_f32 v22, v22, v203, v219
	v_cvt_pk_bf16_f32 v239, v22, s0
	s_add_u32 vcc_lo, s98, s100
	s_addc_u32 vcc_hi, s99, 0
	global_store_short v24, v239, vcc
	s_add_i32 s100, s100, s101
	v_fma_f32 v22, v22, v204, v220
	v_cvt_pk_bf16_f32 v23, v22, s0
	s_add_u32 vcc_lo, s98, s100
	s_addc_u32 vcc_hi, s99, 0
	global_store_short v24, v23, vcc
	s_add_i32 s100, s100, s101
	v_fma_f32 v22, v22, v205, v221
	v_cvt_pk_bf16_f32 v239, v22, s0
	s_add_u32 vcc_lo, s98, s100
	s_addc_u32 vcc_hi, s99, 0
	global_store_short v24, v239, vcc
	s_add_i32 s100, s100, s101
	s_cmp_eq_u32 s45, 18
	s_cbranch_scc1 .Lfz_noload
	s_min_u32 s100, s45, 16
	s_bfe_u32 s101, s37, 0x10001
	s_cmp_eq_u32 s101, 0
	s_cbranch_scc1 .Lfz_mc_nx
	s_sub_i32 s101, 19, s100
	s_cmp_lt_u32 s100, 2
	s_cbranch_scc0 .Lfz_mc1_nx
	s_sub_i32 s101, 1, s100
